# phase-1 K-loop: 5-chunk LDS ring (80KB), DMA pieces interleaved with MFMAs, A two stages ahead with counted vmcnt(4); other K-loops LDS-DMA 2-slot; phase-0 row loads issued together
# speedup vs baseline: 1.1054x; 1.0311x over previous
.LBB0_59:
	v_readlane_b32 s56, v237, 3
	v_readlane_b32 s57, v237, 4
	v_readlane_b32 s59, v237, 6
	v_add_u32_e32 v66, 0xffffc000, v72
	v_cmp_gt_i32_e32 vcc, s16, v72
	v_readlane_b32 s58, v237, 5
	v_mov_b32_e32 v68, s59
	v_mov_b32_e32 v69, s57
	v_cndmask_b32_e32 v67, 0, v73, vcc
	v_cndmask_b32_e32 v66, v66, v72, vcc
	v_cndmask_b32_e32 v69, v68, v69, vcc
	v_mov_b32_e32 v68, s58
	v_mov_b32_e32 v144, s56
	v_cndmask_b32_e32 v68, v68, v144, vcc
	v_lshlrev_b64 v[66:67], 12, v[66:67]
	v_lshl_add_u64 v[66:67], v[68:69], 0, v[66:67]
	v_lshl_add_u64 v[66:67], v[66:67], 0, v[70:71]
	global_load_dwordx4 v[146:149], v[66:67], off
	global_load_dwordx4 v[150:153], v[66:67], off offset:1024
	global_load_dwordx4 v[154:157], v[66:67], off offset:2048
	global_load_dwordx4 v[188:191], v[66:67], off offset:3072
	v_lshl_add_u64 v[144:145], s[54:55], 0, v[142:143]
	v_readlane_b32 s60, v237, 7
	v_readlane_b32 s61, v237, 8
	v_readlane_b32 s62, v237, 9
	v_readlane_b32 s63, v237, 10
	v_readlane_b32 s64, v237, 11
	v_readlane_b32 s65, v237, 12
	v_readlane_b32 s66, v237, 13
	v_readlane_b32 s67, v237, 14
	v_readlane_b32 s68, v237, 15
	v_readlane_b32 s69, v237, 16
	v_readlane_b32 s70, v237, 17
	v_readlane_b32 s71, v237, 18
	s_waitcnt vmcnt(3)
	v_cvt_pk_bf16_f32 v68, v146, v147
	v_cvt_pk_bf16_f32 v69, v148, v149
	global_store_dwordx2 v[144:145], v[68:69], off
	s_waitcnt lgkmcnt(0)
	v_pk_mul_f32 v[172:173], v[146:147], v[134:135]
	v_pk_mul_f32 v[174:175], v[146:147], v[122:123]
	v_pk_mul_f32 v[180:181], v[146:147], v[110:111]
	v_pk_mul_f32 v[158:159], v[146:147], v[146:147]
	v_pk_mul_f32 v[182:183], v[146:147], v[98:99]
	v_pk_fma_f32 v[172:173], v[146:147], v[6:7], v[172:173] op_sel:[1,0,0] op_sel_hi:[0,1,1]
	v_pk_fma_f32 v[174:175], v[146:147], v[14:15], v[174:175] op_sel:[1,0,0] op_sel_hi:[0,1,1]
	v_pk_fma_f32 v[180:181], v[146:147], v[22:23], v[180:181] op_sel:[1,0,0] op_sel_hi:[0,1,1]
	v_pk_mul_f32 v[160:161], v[148:149], v[148:149]
	v_mov_b32_e32 v170, v149
	v_pk_fma_f32 v[146:147], v[146:147], v[30:31], v[182:183] op_sel:[1,0,0] op_sel_hi:[0,1,1]
	v_add_f32_e32 v169, v158, v159
	v_pk_fma_f32 v[158:159], v[148:149], v[136:137], v[172:173] op_sel_hi:[0,1,1]
	v_pk_fma_f32 v[172:173], v[148:149], v[124:125], v[174:175] op_sel_hi:[0,1,1]
	v_pk_fma_f32 v[174:175], v[148:149], v[112:113], v[180:181] op_sel_hi:[0,1,1]
	v_pk_fma_f32 v[146:147], v[148:149], v[100:101], v[146:147] op_sel_hi:[0,1,1]
	v_add_f32_e32 v160, v169, v160
	v_pk_fma_f32 v[148:149], v[170:171], v[8:9], v[158:159] op_sel_hi:[0,1,1]
	v_pk_fma_f32 v[158:159], v[170:171], v[16:17], v[172:173] op_sel_hi:[0,1,1]
	v_pk_fma_f32 v[172:173], v[170:171], v[24:25], v[174:175] op_sel_hi:[0,1,1]
	v_add_f32_e32 v169, v160, v161
	v_pk_add_f32 v[160:161], v[172:173], 0 op_sel_hi:[1,0]
	v_pk_fma_f32 v[146:147], v[170:171], v[32:33], v[146:147] op_sel_hi:[0,1,1]
	v_pk_add_f32 v[148:149], v[148:149], 0 op_sel_hi:[1,0]
	v_pk_add_f32 v[158:159], v[158:159], 0 op_sel_hi:[1,0]
	v_pk_add_f32 v[146:147], v[146:147], 0 op_sel_hi:[1,0]
	s_waitcnt vmcnt(3)
	v_cvt_pk_bf16_f32 v68, v150, v151
	v_cvt_pk_bf16_f32 v69, v152, v153
	global_store_dwordx2 v[144:145], v[68:69], off offset:512
	v_pk_mul_f32 v[172:173], v[150:151], v[150:151]
	v_pk_mul_f32 v[180:181], v[150:151], v[132:133]
	v_pk_mul_f32 v[182:183], v[150:151], v[120:121]
	v_pk_mul_f32 v[184:185], v[150:151], v[108:109]
	v_pk_mul_f32 v[186:187], v[150:151], v[96:97]
	v_pk_mul_f32 v[174:175], v[152:153], v[152:153]
	v_pk_fma_f32 v[180:181], v[150:151], v[2:3], v[180:181] op_sel:[1,0,0] op_sel_hi:[0,1,1]
	v_pk_fma_f32 v[182:183], v[150:151], v[10:11], v[182:183] op_sel:[1,0,0] op_sel_hi:[0,1,1]
	v_pk_fma_f32 v[184:185], v[150:151], v[18:19], v[184:185] op_sel:[1,0,0] op_sel_hi:[0,1,1]
	v_pk_fma_f32 v[150:151], v[150:151], v[26:27], v[186:187] op_sel:[1,0,0] op_sel_hi:[0,1,1]
	v_add_f32_e32 v177, v172, v173
	v_mov_b32_e32 v170, v153
	v_pk_fma_f32 v[172:173], v[152:153], v[4:5], v[180:181] op_sel_hi:[0,1,1]
	v_pk_fma_f32 v[180:181], v[152:153], v[12:13], v[182:183] op_sel_hi:[0,1,1]
	v_pk_fma_f32 v[182:183], v[152:153], v[20:21], v[184:185] op_sel_hi:[0,1,1]
	v_pk_fma_f32 v[150:151], v[152:153], v[28:29], v[150:151] op_sel_hi:[0,1,1]
	v_add_f32_e32 v152, v177, v174
	v_add_f32_e32 v177, v152, v175
	v_pk_fma_f32 v[152:153], v[170:171], v[130:131], v[172:173] op_sel_hi:[0,1,1]
	v_pk_fma_f32 v[172:173], v[170:171], v[118:119], v[180:181] op_sel_hi:[0,1,1]
	v_pk_fma_f32 v[174:175], v[170:171], v[106:107], v[182:183] op_sel_hi:[0,1,1]
	v_pk_fma_f32 v[150:151], v[170:171], v[94:95], v[150:151] op_sel_hi:[0,1,1]
	v_pk_add_f32 v[148:149], v[148:149], v[152:153]
	v_pk_add_f32 v[152:153], v[158:159], v[172:173]
	v_pk_add_f32 v[158:159], v[160:161], v[174:175]
	v_pk_add_f32 v[146:147], v[146:147], v[150:151]
	v_add_f32_e32 v169, v169, v177
	s_waitcnt vmcnt(3)
	v_cvt_pk_bf16_f32 v68, v154, v155
	v_cvt_pk_bf16_f32 v69, v156, v157
	global_store_dwordx2 v[144:145], v[68:69], off offset:1024
	v_pk_mul_f32 v[150:151], v[154:155], v[154:155]
	v_pk_mul_f32 v[172:173], v[154:155], v[128:129]
	v_pk_mul_f32 v[174:175], v[154:155], v[116:117]
	v_pk_mul_f32 v[180:181], v[154:155], v[104:105]
	v_pk_mul_f32 v[182:183], v[154:155], v[92:93]
	v_pk_mul_f32 v[160:161], v[156:157], v[156:157]
	v_pk_fma_f32 v[172:173], v[154:155], v[34:35], v[172:173] op_sel:[1,0,0] op_sel_hi:[0,1,1]
	v_pk_fma_f32 v[174:175], v[154:155], v[42:43], v[174:175] op_sel:[1,0,0] op_sel_hi:[0,1,1]
	v_pk_fma_f32 v[180:181], v[154:155], v[50:51], v[180:181] op_sel:[1,0,0] op_sel_hi:[0,1,1]
	v_pk_fma_f32 v[154:155], v[154:155], v[58:59], v[182:183] op_sel:[1,0,0] op_sel_hi:[0,1,1]
	v_add_f32_e32 v150, v150, v151
	v_mov_b32_e32 v170, v157
	v_add_f32_e32 v160, v150, v160
	v_pk_fma_f32 v[150:151], v[156:157], v[36:37], v[172:173] op_sel_hi:[0,1,1]
	v_pk_fma_f32 v[172:173], v[156:157], v[44:45], v[174:175] op_sel_hi:[0,1,1]
	v_pk_fma_f32 v[174:175], v[156:157], v[52:53], v[180:181] op_sel_hi:[0,1,1]
	v_pk_fma_f32 v[154:155], v[156:157], v[60:61], v[154:155] op_sel_hi:[0,1,1]
	v_add_f32_e32 v177, v160, v161
	v_pk_fma_f32 v[150:151], v[170:171], v[74:75], v[150:151] op_sel_hi:[0,1,1]
	v_pk_fma_f32 v[156:157], v[170:171], v[78:79], v[172:173] op_sel_hi:[0,1,1]
	v_pk_fma_f32 v[160:161], v[170:171], v[82:83], v[174:175] op_sel_hi:[0,1,1]
	v_pk_fma_f32 v[154:155], v[170:171], v[86:87], v[154:155] op_sel_hi:[0,1,1]
	v_pk_add_f32 v[148:149], v[148:149], v[150:151]
	v_pk_add_f32 v[150:151], v[152:153], v[156:157]
	v_pk_add_f32 v[152:153], v[158:159], v[160:161]
	v_pk_add_f32 v[146:147], v[146:147], v[154:155]
	v_add_f32_e32 v169, v169, v177
	s_waitcnt vmcnt(3)
	v_pk_mul_f32 v[154:155], v[188:189], v[188:189]
	v_pk_mul_f32 v[158:159], v[188:189], v[38:39]
	v_pk_mul_f32 v[160:161], v[188:189], v[46:47]
	v_pk_mul_f32 v[172:173], v[188:189], v[54:55]
	v_pk_mul_f32 v[174:175], v[188:189], v[62:63]
	v_pk_mul_f32 v[156:157], v[190:191], v[190:191]
	v_add_f32_e32 v177, v154, v155
	v_pk_fma_f32 v[154:155], v[188:189], v[126:127], v[158:159] op_sel:[0,0,1] op_sel_hi:[1,1,0]
	v_pk_fma_f32 v[158:159], v[188:189], v[114:115], v[160:161] op_sel:[0,0,1] op_sel_hi:[1,1,0]
	v_pk_fma_f32 v[160:161], v[188:189], v[102:103], v[172:173] op_sel:[0,0,1] op_sel_hi:[1,1,0]
	v_pk_fma_f32 v[172:173], v[188:189], v[90:91], v[174:175] op_sel:[0,0,1] op_sel_hi:[1,1,0]
	v_mov_b32_e32 v170, v191
	v_add_f32_e32 v156, v177, v156
	v_pk_fma_f32 v[154:155], v[190:191], v[76:77], v[154:155] op_sel_hi:[0,1,1]
	v_pk_fma_f32 v[158:159], v[190:191], v[80:81], v[158:159] op_sel_hi:[0,1,1]
	v_pk_fma_f32 v[160:161], v[190:191], v[84:85], v[160:161] op_sel_hi:[0,1,1]
	v_pk_fma_f32 v[172:173], v[190:191], v[88:89], v[172:173] op_sel_hi:[0,1,1]
	v_add_f32_e32 v174, v156, v157
	v_pk_fma_f32 v[154:155], v[170:171], v[40:41], v[154:155] op_sel_hi:[0,1,1]
	v_pk_fma_f32 v[156:157], v[170:171], v[48:49], v[158:159] op_sel_hi:[0,1,1]
	v_pk_fma_f32 v[158:159], v[170:171], v[56:57], v[160:161] op_sel_hi:[0,1,1]
	v_pk_fma_f32 v[160:161], v[170:171], v[64:65], v[172:173] op_sel_hi:[0,1,1]
	v_add_f32_e32 v169, v169, v174
	v_pk_add_f32 v[148:149], v[148:149], v[154:155]
	v_pk_add_f32 v[150:151], v[150:151], v[156:157]
	v_pk_add_f32 v[152:153], v[152:153], v[158:159]
	v_pk_add_f32 v[146:147], v[146:147], v[160:161]
	ds_bpermute_b32 v170, v162, v169
	ds_bpermute_b32 v154, v162, v148
	ds_bpermute_b32 v155, v162, v149
	ds_bpermute_b32 v156, v162, v150
	ds_bpermute_b32 v157, v162, v151
	ds_bpermute_b32 v158, v162, v152
	ds_bpermute_b32 v159, v162, v153
	ds_bpermute_b32 v160, v162, v146
	ds_bpermute_b32 v161, v162, v147
	s_waitcnt lgkmcnt(8)
	v_add_f32_e32 v169, v169, v170
	s_waitcnt lgkmcnt(6)
	v_pk_add_f32 v[148:149], v[148:149], v[154:155]
	s_waitcnt lgkmcnt(4)
	v_pk_add_f32 v[150:151], v[150:151], v[156:157]
	s_waitcnt lgkmcnt(2)
	v_pk_add_f32 v[152:153], v[152:153], v[158:159]
	s_waitcnt lgkmcnt(0)
	v_pk_add_f32 v[146:147], v[146:147], v[160:161]
	ds_bpermute_b32 v170, v163, v169
	ds_bpermute_b32 v154, v163, v148
	ds_bpermute_b32 v155, v163, v149
	ds_bpermute_b32 v156, v163, v150
	ds_bpermute_b32 v157, v163, v151
	ds_bpermute_b32 v158, v163, v152
	ds_bpermute_b32 v159, v163, v153
	ds_bpermute_b32 v160, v163, v146
	ds_bpermute_b32 v161, v163, v147
	s_waitcnt lgkmcnt(8)
	v_add_f32_e32 v169, v169, v170
	s_waitcnt lgkmcnt(6)
	v_pk_add_f32 v[148:149], v[148:149], v[154:155]
	s_waitcnt lgkmcnt(4)
	v_pk_add_f32 v[150:151], v[150:151], v[156:157]
	s_waitcnt lgkmcnt(2)
	v_pk_add_f32 v[152:153], v[152:153], v[158:159]
	s_waitcnt lgkmcnt(0)
	v_pk_add_f32 v[146:147], v[146:147], v[160:161]
	ds_bpermute_b32 v170, v164, v169
	ds_bpermute_b32 v154, v164, v148
	ds_bpermute_b32 v155, v164, v149
	ds_bpermute_b32 v156, v164, v150
	ds_bpermute_b32 v157, v164, v151
	ds_bpermute_b32 v158, v164, v152
	ds_bpermute_b32 v159, v164, v153
	ds_bpermute_b32 v160, v164, v146
	ds_bpermute_b32 v161, v164, v147
	s_waitcnt lgkmcnt(8)
	v_add_f32_e32 v169, v169, v170
	s_waitcnt lgkmcnt(6)
	v_pk_add_f32 v[148:149], v[148:149], v[154:155]
	s_waitcnt lgkmcnt(4)
	v_pk_add_f32 v[150:151], v[150:151], v[156:157]
	s_waitcnt lgkmcnt(2)
	v_pk_add_f32 v[152:153], v[152:153], v[158:159]
	s_waitcnt lgkmcnt(0)
	v_pk_add_f32 v[146:147], v[146:147], v[160:161]
	ds_bpermute_b32 v170, v165, v169
	ds_bpermute_b32 v154, v165, v148
	ds_bpermute_b32 v155, v165, v149
	ds_bpermute_b32 v156, v165, v150
	ds_bpermute_b32 v157, v165, v151
	ds_bpermute_b32 v158, v165, v152
	ds_bpermute_b32 v159, v165, v153
	ds_bpermute_b32 v160, v165, v146
	ds_bpermute_b32 v161, v165, v147
	s_waitcnt lgkmcnt(8)
	v_add_f32_e32 v169, v169, v170
	s_waitcnt lgkmcnt(6)
	v_pk_add_f32 v[148:149], v[148:149], v[154:155]
	s_waitcnt lgkmcnt(4)
	v_pk_add_f32 v[150:151], v[150:151], v[156:157]
	s_waitcnt lgkmcnt(2)
	v_pk_add_f32 v[152:153], v[152:153], v[158:159]
	s_waitcnt lgkmcnt(0)
	v_pk_add_f32 v[158:159], v[146:147], v[160:161]
	ds_bpermute_b32 v156, v166, v169
	ds_bpermute_b32 v146, v166, v148
	ds_bpermute_b32 v147, v166, v149
	ds_bpermute_b32 v154, v166, v150
	ds_bpermute_b32 v155, v166, v151
	ds_bpermute_b32 v160, v166, v152
	ds_bpermute_b32 v161, v166, v153
	ds_bpermute_b32 v172, v166, v158
	ds_bpermute_b32 v173, v166, v159
	s_waitcnt lgkmcnt(8)
	v_add_f32_e32 v169, v169, v156
	s_waitcnt lgkmcnt(6)
	v_pk_add_f32 v[156:157], v[148:149], v[146:147]
	s_waitcnt lgkmcnt(4)
	v_pk_add_f32 v[154:155], v[150:151], v[154:155]
	s_waitcnt lgkmcnt(2)
	v_pk_add_f32 v[146:147], v[152:153], v[160:161]
	s_waitcnt lgkmcnt(0)
	v_pk_add_f32 v[148:149], v[158:159], v[172:173]
	ds_bpermute_b32 v170, v167, v169
	ds_bpermute_b32 v160, v167, v156
	ds_bpermute_b32 v161, v167, v157
	ds_bpermute_b32 v158, v167, v154
	ds_bpermute_b32 v159, v167, v155
	ds_bpermute_b32 v150, v167, v146
	ds_bpermute_b32 v151, v167, v147
	ds_bpermute_b32 v152, v167, v148
	ds_bpermute_b32 v153, v167, v149
	v_cvt_pk_bf16_f32 v66, v188, v189
	v_cvt_pk_bf16_f32 v67, v190, v191
	global_store_dwordx2 v[144:145], v[66:67], off offset:1536
	s_and_saveexec_b64 s[14:15], s[4:5]
	s_cbranch_execz .LBB0_58
	s_waitcnt lgkmcnt(8)
	v_add_f32_e32 v66, v169, v170
	v_fmamk_f32 v66, v66, 0x3a800000, v168
	v_mul_f32_e32 v67, 0x4b800000, v66
	v_cmp_gt_f32_e32 vcc, s17, v66
	v_lshl_add_u64 v[144:145], s[54:55], 0, v[140:141]
	s_nop 0
	v_cndmask_b32_e32 v66, v66, v67, vcc
	v_rsq_f32_e32 v68, v66
	v_lshl_add_u64 v[66:67], s[54:55], 0, v[138:139]
	v_mul_f32_e32 v69, 0x45800000, v68
	v_cndmask_b32_e32 v170, v68, v69, vcc
	global_store_dword v[66:67], v170, off
	s_waitcnt lgkmcnt(6)
	v_pk_add_f32 v[66:67], v[156:157], v[160:161]
	s_waitcnt lgkmcnt(4)
	v_pk_add_f32 v[68:69], v[154:155], v[158:159]
	v_add_co_u32_e32 v144, vcc, 0xf291000, v144
	v_pk_mul_f32 v[66:67], v[66:67], v[170:171] op_sel_hi:[1,0]
	v_pk_mul_f32 v[68:69], v[170:171], v[68:69] op_sel_hi:[0,1]
	v_addc_co_u32_e32 v145, vcc, 0, v145, vcc
	global_store_dwordx4 v[144:145], v[66:69], off
	s_waitcnt lgkmcnt(2)
	s_nop 0
	v_pk_add_f32 v[66:67], v[146:147], v[150:151]
	s_waitcnt lgkmcnt(0)
	v_pk_add_f32 v[68:69], v[148:149], v[152:153]
	v_pk_mul_f32 v[66:67], v[170:171], v[66:67] op_sel_hi:[0,1]
	v_pk_mul_f32 v[68:69], v[170:171], v[68:69] op_sel_hi:[0,1]
	global_store_dwordx4 v[144:145], v[66:69], off offset:16
	s_branch .LBB0_58

.LBB0_112:
	v_writelane_b32 v237, s48, 51
	v_writelane_b32 v237, s44, 52
	s_nop 1
	v_writelane_b32 v237, s45, 53
	s_or_b64 exec, exec, s[0:1]
	s_add_u32 s74, s54, 0x2200000
	s_addc_u32 s75, s55, 0
	s_and_b32 s0, s72, 7
	s_cmp_lg_u32 s0, 0
	s_cselect_b64 s[50:51], -1, 0
	s_ashr_i32 s2, s96, 3
	s_ashr_i32 s3, s72, 3
	s_and_b32 s1, s96, 7
	s_cmp_eq_u32 s0, 0
	s_cselect_b64 s[4:5], -1, 0
	v_writelane_b32 v237, s1, 54
	s_mul_i32 s19, s1, 17
	v_writelane_b32 v237, s4, 55
	s_and_b64 s[0:1], s[4:5], exec
	s_movk_i32 s0, 0x1dc
	v_writelane_b32 v237, s5, 56
	s_cselect_b32 s49, s2, s96
	s_cselect_b32 s12, s0, 0xee0
	v_writelane_b32 v237, s3, 57
	s_cselect_b32 s48, s3, s72
	s_cmp_ge_i32 s49, s12
	v_and_b32_e32 v174, 15, v0
	s_barrier
	v_writelane_b32 v237, s2, 58
	s_cbranch_scc1 .LBB0_130
	v_lshrrev_b32_e32 v8, 3, v0
	v_lshlrev_b32_e32 v2, 11, v8
	v_mov_b32_e32 v3, 0
	v_lshl_add_u64 v[4:5], s[54:55], 0, v[2:3]
	v_lshlrev_b32_e32 v2, 4, v0
	v_and_b32_e32 v2, 0x70, v2
	v_lshl_add_u64 v[98:99], v[4:5], 0, v[2:3]
	v_xor_b32_e32 v4, v8, v0
	s_movk_i32 s4, 0x70
	v_lshlrev_b32_e32 v2, 7, v8
	v_lshlrev_b32_e32 v4, 4, v4
	v_lshrrev_b32_e32 v6, 4, v0
	v_and_or_b32 v108, v4, s4, v2
	v_and_b32_e32 v4, 7, v0
	v_bitop3_b32 v5, v6, v4, 3 bitop3:0x6c
	v_bfe_u32 v7, v0, 4, 2
	v_lshlrev_b32_e32 v109, 4, v5
	v_lshlrev_b32_e32 v5, 7, v0
	v_and_b32_e32 v112, 0x2780, v5
	v_bitop3_b32 v5, v7, v4, 4 bitop3:0x36
	s_mov_b64 s[2:3], 0xe680000
	v_lshrrev_b32_e32 v2, 1, v0
	v_lshlrev_b32_e32 v113, 4, v5
	v_and_b32_e32 v5, 64, v0
	v_lshl_add_u64 v[100:101], v[98:99], 0, s[2:3]
	v_and_or_b32 v110, v2, 64, v174
	v_and_or_b32 v114, v2, 24, v5
	v_lshlrev_b32_e32 v2, 8, v0
	v_lshlrev_b32_e32 v4, 4, v4
	s_mov_b32 s2, 0xf800
	s_add_u32 s0, s54, 0xf280000
	v_and_or_b32 v2, v2, s2, v4
	s_addc_u32 s1, s55, 0
	s_add_i32 s13, s19, 9
	v_lshlrev_b32_e32 v111, 7, v110
	v_lshl_add_u64 v[102:103], s[54:55], 0, v[2:3]
	s_mov_b32 s14, 0x10000
	s_mov_b32 s15, 0x20000
	s_mov_b32 s16, 0x30000
	s_movk_i32 s17, 0x1c00
	s_mov_b32 s18, s49
	v_lshrrev_b32_e32 v104, 3, v0
	v_lshlrev_b32_e32 v104, 11, v104
	v_and_b32_e32 v105, 0x70, v108
	v_or_b32_e32 v104, v104, v105
	v_add_u32_e32 v105, 0x10000, v104
	v_add_u32_e32 v106, 0x20000, v104
	v_add_u32_e32 v107, 0x30000, v104
	v_add_u32_e32 v98, v109, v111
	v_add_u32_e32 v99, v113, v111
	v_add_u32_e32 v100, v109, v112
	v_add_u32_e32 v101, v113, v112
	v_lshrrev_b32_e32 v115, 6, v0
	s_nop 1
	v_readfirstlane_b32 s30, v115
	s_nop 3
	s_lshl_b32 s30, s30, 10
	s_branch .LBB0_115

.LBB0_122:
	s_lshl_b32 s4, s4, 7
	s_lshl_b32 s2, s5, 7
	s_lshl_b32 s24, s4, 11
	s_add_u32 s26, s54, s24
	s_addc_u32 s27, s55, 0
	s_lshl_b32 s24, s2, 11
	s_add_u32 s28, s54, s24
	s_addc_u32 s29, s55, 0
	s_add_u32 s28, s28, 0xe680000
	s_addc_u32 s29, s29, 0
	s_barrier
	s_mov_b32 m0, s30
	s_nop 0
	global_load_lds_dwordx4 v104, s[26:27]
	s_add_u32 m0, s30, 0x1000
	s_nop 0
	global_load_lds_dwordx4 v105, s[26:27]
	s_add_u32 m0, s30, 0x2000
	s_nop 0
	global_load_lds_dwordx4 v106, s[26:27]
	s_add_u32 m0, s30, 0x3000
	s_nop 0
	global_load_lds_dwordx4 v107, s[26:27]
	s_add_u32 s31, s30, 0x4000
	s_mov_b32 m0, s31
	s_nop 0
	global_load_lds_dwordx4 v104, s[28:29]
	s_add_u32 m0, s31, 0x1000
	s_nop 0
	global_load_lds_dwordx4 v105, s[28:29]
	s_add_u32 m0, s31, 0x2000
	s_nop 0
	global_load_lds_dwordx4 v106, s[28:29]
	s_add_u32 m0, s31, 0x3000
	s_nop 0
	global_load_lds_dwordx4 v107, s[28:29]
	s_add_u32 s26, s26, 0x80
	s_addc_u32 s27, s27, 0
	s_add_u32 s31, s30, 0x8000
	s_mov_b32 m0, s31
	s_nop 0
	global_load_lds_dwordx4 v104, s[26:27]
	s_add_u32 m0, s31, 0x1000
	s_nop 0
	global_load_lds_dwordx4 v105, s[26:27]
	s_add_u32 m0, s31, 0x2000
	s_nop 0
	global_load_lds_dwordx4 v106, s[26:27]
	s_add_u32 m0, s31, 0x3000
	s_nop 0
	global_load_lds_dwordx4 v107, s[26:27]
	v_mov_b32_e32 v2, 0
	v_mov_b32_e32 v3, v2
	v_mov_b32_e32 v4, v2
	v_mov_b32_e32 v5, v2
	v_mov_b32_e32 v6, v2
	v_mov_b32_e32 v7, v2
	v_mov_b32_e32 v8, v2
	v_mov_b32_e32 v9, v2
	v_mov_b32_e32 v10, v2
	v_mov_b32_e32 v11, v2
	v_mov_b32_e32 v12, v2
	v_mov_b32_e32 v13, v2
	v_mov_b32_e32 v14, v2
	v_mov_b32_e32 v15, v2
	v_mov_b32_e32 v16, v2
	v_mov_b32_e32 v17, v2
	v_mov_b32_e32 v18, v2
	v_mov_b32_e32 v19, v2
	v_mov_b32_e32 v20, v2
	v_mov_b32_e32 v21, v2
	v_mov_b32_e32 v22, v2
	v_mov_b32_e32 v23, v2
	v_mov_b32_e32 v24, v2
	v_mov_b32_e32 v25, v2
	v_mov_b32_e32 v26, v2
	v_mov_b32_e32 v27, v2
	v_mov_b32_e32 v28, v2
	v_mov_b32_e32 v29, v2
	v_mov_b32_e32 v30, v2
	v_mov_b32_e32 v31, v2
	v_mov_b32_e32 v32, v2
	v_mov_b32_e32 v33, v2
	v_mov_b32_e32 v34, v2
	v_mov_b32_e32 v35, v2
	v_mov_b32_e32 v36, v2
	v_mov_b32_e32 v37, v2
	v_mov_b32_e32 v46, v2
	v_mov_b32_e32 v47, v2
	v_mov_b32_e32 v48, v2
	v_mov_b32_e32 v49, v2
	v_mov_b32_e32 v50, v2
	v_mov_b32_e32 v51, v2
	v_mov_b32_e32 v52, v2
	v_mov_b32_e32 v53, v2
	v_mov_b32_e32 v58, v2
	v_mov_b32_e32 v59, v2
	v_mov_b32_e32 v60, v2
	v_mov_b32_e32 v61, v2
	v_mov_b32_e32 v82, v2
	v_mov_b32_e32 v83, v2
	v_mov_b32_e32 v84, v2
	v_mov_b32_e32 v85, v2
	v_mov_b32_e32 v86, v2
	v_mov_b32_e32 v87, v2
	v_mov_b32_e32 v88, v2
	v_mov_b32_e32 v89, v2
	v_mov_b32_e32 v90, v2
	v_mov_b32_e32 v91, v2
	v_mov_b32_e32 v92, v2
	v_mov_b32_e32 v93, v2
	v_mov_b32_e32 v94, v2
	v_mov_b32_e32 v95, v2
	v_mov_b32_e32 v96, v2
	v_mov_b32_e32 v97, v2
	s_mov_b32 s3, 0
	s_mov_b32 s10, 0
	s_mov_b32 s11, 0x4000
	s_waitcnt vmcnt(4)
	s_barrier
.Lg1_loop:
	v_add_u32_e32 v136, s11, v100
	ds_read_b128 v[116:119], v136
	v_add_u32_e32 v115, s10, v98
	ds_read_b128 v[120:123], v136 offset:2048
	ds_read_b128 v[124:127], v115
	ds_read_b128 v[128:131], v115 offset:2048
	ds_read_b128 v[132:135], v136 offset:4096
	ds_read_b128 v[136:139], v136 offset:6144
	s_add_u32 s28, s28, 0x80
	s_addc_u32 s29, s29, 0
	s_add_u32 s31, s10, 0xc000
	s_sub_u32 s25, s31, 0x14000
	s_cmp_ge_u32 s31, 0x14000
	s_cselect_b32 s31, s25, s31
	s_add_u32 s31, s31, s30
	s_add_u32 s26, s26, 0x80
	s_addc_u32 s27, s27, 0
	s_add_u32 s24, s10, 0x10000
	s_sub_u32 s25, s24, 0x14000
	s_cmp_ge_u32 s24, 0x14000
	s_cselect_b32 s24, s25, s24
	s_add_u32 s24, s24, s30
	s_mov_b32 m0, s31
	s_nop 0
	global_load_lds_dwordx4 v104, s[28:29]
	s_waitcnt lgkmcnt(3)
	v_mfma_f32_16x16x32_bf16 v[90:93], v[120:123], v[124:127], v[90:93]
	v_mfma_f32_16x16x32_bf16 v[94:97], v[116:119], v[124:127], v[94:97]
	s_waitcnt lgkmcnt(1)
	v_mfma_f32_16x16x32_bf16 v[86:89], v[132:135], v[124:127], v[86:89]
	s_waitcnt lgkmcnt(0)
	v_mfma_f32_16x16x32_bf16 v[82:85], v[136:139], v[124:127], v[82:85]
	s_add_u32 m0, s31, 0x1000
	s_nop 0
	global_load_lds_dwordx4 v105, s[28:29]
	v_mfma_f32_16x16x32_bf16 v[58:61], v[116:119], v[128:131], v[58:61]
	v_mfma_f32_16x16x32_bf16 v[50:53], v[120:123], v[128:131], v[50:53]
	v_mfma_f32_16x16x32_bf16 v[46:49], v[132:135], v[128:131], v[46:49]
	v_mfma_f32_16x16x32_bf16 v[34:37], v[136:139], v[128:131], v[34:37]
	ds_read_b128 v[124:127], v115 offset:4096
	ds_read_b128 v[128:131], v115 offset:6144
	v_add_u32_e32 v140, s11, v101
	s_add_u32 m0, s31, 0x2000
	s_nop 0
	global_load_lds_dwordx4 v106, s[28:29]
	s_waitcnt lgkmcnt(1)
	v_mfma_f32_16x16x32_bf16 v[30:33], v[116:119], v[124:127], v[30:33]
	v_add_u32_e32 v115, s10, v99
	v_mfma_f32_16x16x32_bf16 v[26:29], v[120:123], v[124:127], v[26:29]
	v_mfma_f32_16x16x32_bf16 v[22:25], v[132:135], v[124:127], v[22:25]
	v_mfma_f32_16x16x32_bf16 v[18:21], v[136:139], v[124:127], v[18:21]
	s_add_u32 m0, s31, 0x3000
	s_nop 0
	global_load_lds_dwordx4 v107, s[28:29]
	s_waitcnt lgkmcnt(0)
	v_mfma_f32_16x16x32_bf16 v[14:17], v[116:119], v[128:131], v[14:17]
	ds_read_b128 v[116:119], v140
	v_mfma_f32_16x16x32_bf16 v[10:13], v[120:123], v[128:131], v[10:13]
	v_mfma_f32_16x16x32_bf16 v[6:9], v[132:135], v[128:131], v[6:9]
	v_mfma_f32_16x16x32_bf16 v[2:5], v[136:139], v[128:131], v[2:5]
	ds_read_b128 v[120:123], v140 offset:2048
	ds_read_b128 v[124:127], v115
	ds_read_b128 v[128:131], v115 offset:2048
	ds_read_b128 v[132:135], v140 offset:4096
	ds_read_b128 v[136:139], v140 offset:6144
	s_mov_b32 m0, s24
	s_nop 0
	global_load_lds_dwordx4 v104, s[26:27]
	s_waitcnt lgkmcnt(3)
	v_mfma_f32_16x16x32_bf16 v[94:97], v[116:119], v[124:127], v[94:97]
	v_mfma_f32_16x16x32_bf16 v[90:93], v[120:123], v[124:127], v[90:93]
	s_waitcnt lgkmcnt(1)
	v_mfma_f32_16x16x32_bf16 v[86:89], v[132:135], v[124:127], v[86:89]
	s_waitcnt lgkmcnt(0)
	v_mfma_f32_16x16x32_bf16 v[82:85], v[136:139], v[124:127], v[82:85]
	s_add_u32 m0, s24, 0x1000
	s_nop 0
	global_load_lds_dwordx4 v105, s[26:27]
	v_mfma_f32_16x16x32_bf16 v[58:61], v[116:119], v[128:131], v[58:61]
	v_mfma_f32_16x16x32_bf16 v[50:53], v[120:123], v[128:131], v[50:53]
	v_mfma_f32_16x16x32_bf16 v[46:49], v[132:135], v[128:131], v[46:49]
	v_mfma_f32_16x16x32_bf16 v[34:37], v[136:139], v[128:131], v[34:37]
	ds_read_b128 v[124:127], v115 offset:4096
	ds_read_b128 v[128:131], v115 offset:6144
	s_add_u32 m0, s24, 0x2000
	s_nop 0
	global_load_lds_dwordx4 v106, s[26:27]
	s_waitcnt lgkmcnt(1)
	v_mfma_f32_16x16x32_bf16 v[30:33], v[116:119], v[124:127], v[30:33]
	v_mfma_f32_16x16x32_bf16 v[26:29], v[120:123], v[124:127], v[26:29]
	v_mfma_f32_16x16x32_bf16 v[22:25], v[132:135], v[124:127], v[22:25]
	v_mfma_f32_16x16x32_bf16 v[18:21], v[136:139], v[124:127], v[18:21]
	s_add_u32 m0, s24, 0x3000
	s_nop 0
	global_load_lds_dwordx4 v107, s[26:27]
	s_waitcnt lgkmcnt(0)
	v_mfma_f32_16x16x32_bf16 v[14:17], v[116:119], v[128:131], v[14:17]
	v_mfma_f32_16x16x32_bf16 v[10:13], v[120:123], v[128:131], v[10:13]
	v_mfma_f32_16x16x32_bf16 v[6:9], v[132:135], v[128:131], v[6:9]
	v_mfma_f32_16x16x32_bf16 v[2:5], v[136:139], v[128:131], v[2:5]
	s_add_u32 s10, s10, 0x8000
	s_sub_u32 s25, s10, 0x14000
	s_cmp_ge_u32 s10, 0x14000
	s_cselect_b32 s10, s25, s10
	s_add_u32 s11, s11, 0x8000
	s_sub_u32 s25, s11, 0x14000
	s_cmp_ge_u32 s11, 0x14000
	s_cselect_b32 s11, s25, s11
	s_waitcnt vmcnt(4)
	s_barrier
	s_add_i32 s3, s3, 1
	s_cmp_lg_u32 s3, 14
	s_cbranch_scc1 .Lg1_loop
	v_add_u32_e32 v136, s11, v100
	ds_read_b128 v[116:119], v136
	v_add_u32_e32 v115, s10, v98
	ds_read_b128 v[120:123], v136 offset:2048
	ds_read_b128 v[124:127], v115
	ds_read_b128 v[128:131], v115 offset:2048
	ds_read_b128 v[132:135], v136 offset:4096
	ds_read_b128 v[136:139], v136 offset:6144
	s_add_u32 s28, s28, 0x80
	s_addc_u32 s29, s29, 0
	s_add_u32 s31, s10, 0xc000
	s_sub_u32 s25, s31, 0x14000
	s_cmp_ge_u32 s31, 0x14000
	s_cselect_b32 s31, s25, s31
	s_add_u32 s31, s31, s30
	s_mov_b32 m0, s31
	s_nop 0
	global_load_lds_dwordx4 v104, s[28:29]
	s_waitcnt lgkmcnt(3)
	v_mfma_f32_16x16x32_bf16 v[90:93], v[120:123], v[124:127], v[90:93]
	v_mfma_f32_16x16x32_bf16 v[94:97], v[116:119], v[124:127], v[94:97]
	s_waitcnt lgkmcnt(1)
	v_mfma_f32_16x16x32_bf16 v[86:89], v[132:135], v[124:127], v[86:89]
	s_waitcnt lgkmcnt(0)
	v_mfma_f32_16x16x32_bf16 v[82:85], v[136:139], v[124:127], v[82:85]
	s_add_u32 m0, s31, 0x1000
	s_nop 0
	global_load_lds_dwordx4 v105, s[28:29]
	v_mfma_f32_16x16x32_bf16 v[58:61], v[116:119], v[128:131], v[58:61]
	v_mfma_f32_16x16x32_bf16 v[50:53], v[120:123], v[128:131], v[50:53]
	v_mfma_f32_16x16x32_bf16 v[46:49], v[132:135], v[128:131], v[46:49]
	v_mfma_f32_16x16x32_bf16 v[34:37], v[136:139], v[128:131], v[34:37]
	ds_read_b128 v[124:127], v115 offset:4096
	ds_read_b128 v[128:131], v115 offset:6144
	v_add_u32_e32 v140, s11, v101
	s_add_u32 m0, s31, 0x2000
	s_nop 0
	global_load_lds_dwordx4 v106, s[28:29]
	s_waitcnt lgkmcnt(1)
	v_mfma_f32_16x16x32_bf16 v[30:33], v[116:119], v[124:127], v[30:33]
	v_add_u32_e32 v115, s10, v99
	v_mfma_f32_16x16x32_bf16 v[26:29], v[120:123], v[124:127], v[26:29]
	v_mfma_f32_16x16x32_bf16 v[22:25], v[132:135], v[124:127], v[22:25]
	v_mfma_f32_16x16x32_bf16 v[18:21], v[136:139], v[124:127], v[18:21]
	s_add_u32 m0, s31, 0x3000
	s_nop 0
	global_load_lds_dwordx4 v107, s[28:29]
	s_waitcnt lgkmcnt(0)
	v_mfma_f32_16x16x32_bf16 v[14:17], v[116:119], v[128:131], v[14:17]
	ds_read_b128 v[116:119], v140
	v_mfma_f32_16x16x32_bf16 v[10:13], v[120:123], v[128:131], v[10:13]
	v_mfma_f32_16x16x32_bf16 v[6:9], v[132:135], v[128:131], v[6:9]
	v_mfma_f32_16x16x32_bf16 v[2:5], v[136:139], v[128:131], v[2:5]
	ds_read_b128 v[120:123], v140 offset:2048
	ds_read_b128 v[124:127], v115
	ds_read_b128 v[128:131], v115 offset:2048
	ds_read_b128 v[132:135], v140 offset:4096
	ds_read_b128 v[136:139], v140 offset:6144
	s_waitcnt lgkmcnt(3)
	v_mfma_f32_16x16x32_bf16 v[94:97], v[116:119], v[124:127], v[94:97]
	v_mfma_f32_16x16x32_bf16 v[90:93], v[120:123], v[124:127], v[90:93]
	s_waitcnt lgkmcnt(1)
	v_mfma_f32_16x16x32_bf16 v[86:89], v[132:135], v[124:127], v[86:89]
	s_waitcnt lgkmcnt(0)
	v_mfma_f32_16x16x32_bf16 v[82:85], v[136:139], v[124:127], v[82:85]
	v_mfma_f32_16x16x32_bf16 v[58:61], v[116:119], v[128:131], v[58:61]
	v_mfma_f32_16x16x32_bf16 v[50:53], v[120:123], v[128:131], v[50:53]
	v_mfma_f32_16x16x32_bf16 v[46:49], v[132:135], v[128:131], v[46:49]
	v_mfma_f32_16x16x32_bf16 v[34:37], v[136:139], v[128:131], v[34:37]
	ds_read_b128 v[124:127], v115 offset:4096
	ds_read_b128 v[128:131], v115 offset:6144
	s_waitcnt lgkmcnt(1)
	v_mfma_f32_16x16x32_bf16 v[30:33], v[116:119], v[124:127], v[30:33]
	v_mfma_f32_16x16x32_bf16 v[26:29], v[120:123], v[124:127], v[26:29]
	v_mfma_f32_16x16x32_bf16 v[22:25], v[132:135], v[124:127], v[22:25]
	v_mfma_f32_16x16x32_bf16 v[18:21], v[136:139], v[124:127], v[18:21]
	s_waitcnt lgkmcnt(0)
	v_mfma_f32_16x16x32_bf16 v[14:17], v[116:119], v[128:131], v[14:17]
	v_mfma_f32_16x16x32_bf16 v[10:13], v[120:123], v[128:131], v[10:13]
	v_mfma_f32_16x16x32_bf16 v[6:9], v[132:135], v[128:131], v[6:9]
	v_mfma_f32_16x16x32_bf16 v[2:5], v[136:139], v[128:131], v[2:5]
	s_add_u32 s10, s10, 0x8000
	s_sub_u32 s25, s10, 0x14000
	s_cmp_ge_u32 s10, 0x14000
	s_cselect_b32 s10, s25, s10
	s_add_u32 s11, s11, 0x8000
	s_sub_u32 s25, s11, 0x14000
	s_cmp_ge_u32 s11, 0x14000
	s_cselect_b32 s11, s25, s11
	s_waitcnt vmcnt(0)
	s_barrier
	v_add_u32_e32 v136, s11, v100
	ds_read_b128 v[116:119], v136
	v_add_u32_e32 v115, s10, v98
	ds_read_b128 v[120:123], v136 offset:2048
	ds_read_b128 v[124:127], v115
	ds_read_b128 v[128:131], v115 offset:2048
	ds_read_b128 v[132:135], v136 offset:4096
	ds_read_b128 v[136:139], v136 offset:6144
	s_waitcnt lgkmcnt(3)
	v_mfma_f32_16x16x32_bf16 v[90:93], v[120:123], v[124:127], v[90:93]
	v_mfma_f32_16x16x32_bf16 v[94:97], v[116:119], v[124:127], v[94:97]
	s_waitcnt lgkmcnt(1)
	v_mfma_f32_16x16x32_bf16 v[86:89], v[132:135], v[124:127], v[86:89]
	s_waitcnt lgkmcnt(0)
	v_mfma_f32_16x16x32_bf16 v[82:85], v[136:139], v[124:127], v[82:85]
	v_mfma_f32_16x16x32_bf16 v[58:61], v[116:119], v[128:131], v[58:61]
	v_mfma_f32_16x16x32_bf16 v[50:53], v[120:123], v[128:131], v[50:53]
	v_mfma_f32_16x16x32_bf16 v[46:49], v[132:135], v[128:131], v[46:49]
	v_mfma_f32_16x16x32_bf16 v[34:37], v[136:139], v[128:131], v[34:37]
	ds_read_b128 v[124:127], v115 offset:4096
	ds_read_b128 v[128:131], v115 offset:6144
	v_add_u32_e32 v140, s11, v101
	s_waitcnt lgkmcnt(1)
	v_mfma_f32_16x16x32_bf16 v[30:33], v[116:119], v[124:127], v[30:33]
	v_add_u32_e32 v115, s10, v99
	v_mfma_f32_16x16x32_bf16 v[26:29], v[120:123], v[124:127], v[26:29]
	v_mfma_f32_16x16x32_bf16 v[22:25], v[132:135], v[124:127], v[22:25]
	v_mfma_f32_16x16x32_bf16 v[18:21], v[136:139], v[124:127], v[18:21]
	s_waitcnt lgkmcnt(0)
	v_mfma_f32_16x16x32_bf16 v[14:17], v[116:119], v[128:131], v[14:17]
	ds_read_b128 v[116:119], v140
	v_mfma_f32_16x16x32_bf16 v[10:13], v[120:123], v[128:131], v[10:13]
	v_mfma_f32_16x16x32_bf16 v[6:9], v[132:135], v[128:131], v[6:9]
	v_mfma_f32_16x16x32_bf16 v[2:5], v[136:139], v[128:131], v[2:5]
	ds_read_b128 v[120:123], v140 offset:2048
	ds_read_b128 v[124:127], v115
	ds_read_b128 v[128:131], v115 offset:2048
	ds_read_b128 v[132:135], v140 offset:4096
	ds_read_b128 v[136:139], v140 offset:6144
	s_waitcnt lgkmcnt(3)
	v_mfma_f32_16x16x32_bf16 v[94:97], v[116:119], v[124:127], v[94:97]
	v_mfma_f32_16x16x32_bf16 v[90:93], v[120:123], v[124:127], v[90:93]
	s_waitcnt lgkmcnt(1)
	v_mfma_f32_16x16x32_bf16 v[86:89], v[132:135], v[124:127], v[86:89]
	s_waitcnt lgkmcnt(0)
	v_mfma_f32_16x16x32_bf16 v[82:85], v[136:139], v[124:127], v[82:85]
	v_mfma_f32_16x16x32_bf16 v[58:61], v[116:119], v[128:131], v[58:61]
	v_mfma_f32_16x16x32_bf16 v[50:53], v[120:123], v[128:131], v[50:53]
	v_mfma_f32_16x16x32_bf16 v[46:49], v[132:135], v[128:131], v[46:49]
	v_mfma_f32_16x16x32_bf16 v[34:37], v[136:139], v[128:131], v[34:37]
	ds_read_b128 v[124:127], v115 offset:4096
	ds_read_b128 v[128:131], v115 offset:6144
	s_waitcnt lgkmcnt(1)
	v_mfma_f32_16x16x32_bf16 v[30:33], v[116:119], v[124:127], v[30:33]
	v_mfma_f32_16x16x32_bf16 v[26:29], v[120:123], v[124:127], v[26:29]
	v_mfma_f32_16x16x32_bf16 v[22:25], v[132:135], v[124:127], v[22:25]
	v_mfma_f32_16x16x32_bf16 v[18:21], v[136:139], v[124:127], v[18:21]
	s_waitcnt lgkmcnt(0)
	v_mfma_f32_16x16x32_bf16 v[14:17], v[116:119], v[128:131], v[14:17]
	v_mfma_f32_16x16x32_bf16 v[10:13], v[120:123], v[128:131], v[10:13]
	v_mfma_f32_16x16x32_bf16 v[6:9], v[132:135], v[128:131], v[6:9]
	v_mfma_f32_16x16x32_bf16 v[2:5], v[136:139], v[128:131], v[2:5]
	s_add_u32 s10, s10, 0x8000
	s_sub_u32 s25, s10, 0x14000
	s_cmp_ge_u32 s10, 0x14000
	s_cselect_b32 s10, s25, s10
	s_add_u32 s11, s11, 0x8000
	s_sub_u32 s25, s11, 0x14000
	s_cmp_ge_u32 s11, 0x14000
	s_cselect_b32 s11, s25, s11
	s_waitcnt vmcnt(0)
	s_barrier
	s_branch .LBB0_114

	.amdhsa_kernel _Z4megaILin1EEv6Params
		.amdhsa_group_segment_fixed_size 81920
		.amdhsa_private_segment_fixed_size 0
		.amdhsa_kernarg_size 456
		.amdhsa_user_sgpr_count 2
		.amdhsa_user_sgpr_dispatch_ptr 0
		.amdhsa_user_sgpr_queue_ptr 0
		.amdhsa_user_sgpr_kernarg_segment_ptr 1
		.amdhsa_user_sgpr_dispatch_id 0
		.amdhsa_user_sgpr_kernarg_preload_length 0
		.amdhsa_user_sgpr_kernarg_preload_offset 0
		.amdhsa_user_sgpr_private_segment_size 0
		.amdhsa_uses_dynamic_stack 0
		.amdhsa_enable_private_segment 0
		.amdhsa_system_sgpr_workgroup_id_x 1
		.amdhsa_system_sgpr_workgroup_id_y 0
		.amdhsa_system_sgpr_workgroup_id_z 0
		.amdhsa_system_sgpr_workgroup_info 0
		.amdhsa_system_vgpr_workitem_id 0
		.amdhsa_next_free_vgpr 246
		.amdhsa_next_free_sgpr 102
		.amdhsa_accum_offset 248
		.amdhsa_reserve_vcc 1
		.amdhsa_float_round_mode_32 0
		.amdhsa_float_round_mode_16_64 0
		.amdhsa_float_denorm_mode_32 3
		.amdhsa_float_denorm_mode_16_64 3
		.amdhsa_dx10_clamp 1
		.amdhsa_ieee_mode 1
		.amdhsa_fp16_overflow 0
		.amdhsa_tg_split 0
		.amdhsa_exception_fp_ieee_invalid_op 0
		.amdhsa_exception_fp_denorm_src 0
		.amdhsa_exception_fp_ieee_div_zero 0
		.amdhsa_exception_fp_ieee_overflow 0
		.amdhsa_exception_fp_ieee_underflow 0
		.amdhsa_exception_fp_ieee_inexact 0
		.amdhsa_exception_int_div_zero 0
	.end_amdhsa_kernel

amdhsa.kernels:
  - .agpr_count:     0
    .args:
      - .offset:         0
        .size:           200
        .value_kind:     by_value
      - .offset:         200
        .size:           4
        .value_kind:     hidden_block_count_x
      - .offset:         204
        .size:           4
        .value_kind:     hidden_block_count_y
      - .offset:         208
        .size:           4
        .value_kind:     hidden_block_count_z
      - .offset:         212
        .size:           2
        .value_kind:     hidden_group_size_x
      - .offset:         214
        .size:           2
        .value_kind:     hidden_group_size_y
      - .offset:         216
        .size:           2
        .value_kind:     hidden_group_size_z
      - .offset:         218
        .size:           2
        .value_kind:     hidden_remainder_x
      - .offset:         220
        .size:           2
        .value_kind:     hidden_remainder_y
      - .offset:         222
        .size:           2
        .value_kind:     hidden_remainder_z
      - .offset:         240
        .size:           8
        .value_kind:     hidden_global_offset_x
      - .offset:         248
        .size:           8
        .value_kind:     hidden_global_offset_y
      - .offset:         256
        .size:           8
        .value_kind:     hidden_global_offset_z
      - .offset:         264
        .size:           2
        .value_kind:     hidden_grid_dims
    .group_segment_fixed_size: 81920
    .kernarg_segment_align: 8
    .kernarg_segment_size: 456
    .language:       OpenCL C
    .language_version:
      - 2
      - 0
    .max_flat_workgroup_size: 256
    .name:           _Z4megaILin1EEv6Params
    .private_segment_fixed_size: 0
    .sgpr_count:     108
    .sgpr_spill_count: 277
    .symbol:         _Z4megaILin1EEv6Params.kd
    .uniform_work_group_size: 1
    .uses_dynamic_stack: false
    .vgpr_count:     246
    .vgpr_spill_count: 0
    .wavefront_size: 64
